# in-projection split into two single-tile passes around the P1|P2 grid barrier (round 1 holds every tile mixprep reads); workgroups without a second tile do most of mixprep meanwhile (new item schedule
# speedup vs baseline: 1.0122x; 1.0078x over previous
.LBB0_196:
	s_mov_b32 s6, 1
	s_nop 0
	v_writelane_b32 v255, s6, 10
	s_mov_b32 s14, s2
.Lp1_pass:
	s_and_b32 s11, s14, 7
	s_lshr_b32 s16, s14, 3
	s_lshl_b32 s15, s11, 3
	s_cmp_lt_u32 s16, 24
	s_cbranch_scc0 .Lp1m0_a
	s_mul_i32 s17, s16, 0x5556
	s_lshr_b32 s17, s17, 16
	s_add_i32 s15, s15, s17
	s_mul_i32 s17, s17, 3
	s_sub_i32 s17, s16, s17
	s_add_i32 s10, s17, 2
	s_cmp_eq_u32 s17, 2
	s_cselect_b32 s17, 1, 0
	s_add_i32 s10, s10, s17
	s_branch .Lp1m0_done
.Lp1m0_a:
	s_cmp_lt_u32 s16, 32
	s_cbranch_scc0 .Lp1m0_r2
	s_mov_b32 s10, 4
	s_cmp_ge_u32 s11, 4
	s_cbranch_scc0 .Lp1m0_b
	s_sub_i32 s17, s16, 24
	s_add_i32 s15, s15, s17
	s_branch .Lp1m0_done
.Lp1m0_b:
	s_cmp_lt_u32 s16, 27
	s_cbranch_scc0 .Lp1m0_c
	s_add_i32 s15, s11, 64
	s_sub_i32 s17, s16, 24
	s_add_i32 s10, s17, 2
	s_cmp_eq_u32 s17, 2
	s_cselect_b32 s17, 1, 0
	s_add_i32 s10, s10, s17
	s_branch .Lp1m0_done
.Lp1m0_c:
	s_sub_i32 s17, s16, 27
	s_add_i32 s15, s15, s17
	s_branch .Lp1m0_done
.Lp1m0_r2:
	s_sub_i32 s16, s16, 32
	s_cmp_lt_u32 s16, 16
	s_cbranch_scc0 .Lp1m0_d
	s_lshr_b32 s17, s16, 1
	s_add_i32 s15, s15, s17
	s_and_b32 s10, s16, 1
	s_branch .Lp1m0_done
.Lp1m0_d:
	s_sub_i32 s16, s16, 16
	s_cmp_ge_u32 s11, 4
	s_cbranch_scc0 .Lp1m0_e
	s_add_i32 s15, s11, 60
	s_mov_b32 s10, s16
	s_cmp_eq_u32 s16, 2
	s_cselect_b32 s10, 4, s10
	s_branch .Lp1m0_done
.Lp1m0_e:
	s_add_i32 s15, s15, 5
	s_add_i32 s15, s15, s16
	s_mov_b32 s10, 4
.Lp1m0_done:
	s_lshl_b32 s4, s10, 19
	s_mov_b32 s5, 0
	s_mov_b32 s6, s15
	s_mov_b32 s7, 0
	s_nop 0
	v_writelane_b32 v254, s4, 4
	v_writelane_b32 v254, s5, 5
	v_writelane_b32 v254, s6, 6
	v_writelane_b32 v254, s5, 7
	v_writelane_b32 v254, s10, 11
	v_readlane_b32 s8, v254, 8
	v_readlane_b32 s9, v254, 9
	s_lshl_b64 s[4:5], s[6:7], 19
	s_nop 0
	s_add_u32 s4, s8, s4
	s_addc_u32 s5, s9, s5
	s_nop 0
	v_writelane_b32 v254, s4, 12
	v_writelane_b32 v254, s5, 13
	s_add_u32 s4, s4, 0x40000
	s_addc_u32 s5, s5, 0
	s_nop 0
	v_writelane_b32 v254, s4, 14
	v_writelane_b32 v254, s5, 15
	s_mul_i32 s4, s71, 0x1580000
	v_readlane_b32 s5, v252, 11
	s_add_u32 s4, s5, s4
	v_writelane_b32 v254, s4, 51
	v_readlane_b32 s4, v252, 12
	s_addc_u32 s4, s4, 0
	v_mbcnt_lo_u32_b32 v0, -1, 0
	v_mbcnt_hi_u32_b32 v0, -1, v0
	s_nop 0
	v_writelane_b32 v254, s4, 52
	v_readlane_b32 s4, v252, 13
	v_add_u32_e32 v2, s33, v0
	v_readlane_b32 s5, v252, 14
	s_andn2_b64 vcc, exec, s[4:5]
	v_readfirstlane_b32 s4, v2
	s_cbranch_vccnz .LBB0_212
	v_lshlrev_b32_e32 v0, 4, v2
	v_add_u32_e32 v4, 0x2000, v0
	v_ashrrev_i32_e32 v3, 31, v4
	v_lshrrev_b32_e32 v3, 22, v3
	v_add_u32_e32 v3, v4, v3
	v_ashrrev_i32_e32 v3, 10, v3
	v_mul_i32_i24_e32 v5, 0x400, v3
	v_sub_u32_e32 v4, v4, v5
	v_lshrrev_b32_e32 v5, 4, v4
	v_bitop3_b32 v5, v5, v4, 32 bitop3:0x6c
	v_ashrrev_i32_e32 v4, 31, v5
	v_lshrrev_b32_e32 v4, 26, v4
	v_add_u32_e32 v6, v5, v4
	v_lshlrev_b32_e32 v7, 3, v3
	v_ashrrev_i32_e32 v4, 6, v6
	v_and_b32_e32 v7, -16, v7
	v_add_u32_e32 v7, v4, v7
	v_and_b32_e32 v8, 3, v4
	s_mov_b32 s6, 0x1fffe0
	v_lshrrev_b32_e32 v9, 2, v7
	v_lshlrev_b32_e32 v10, 1, v7
	v_and_b32_e32 v6, 0xc0, v6
	v_and_or_b32 v8, v7, s6, v8
	v_and_b32_e32 v9, 4, v9
	v_and_b32_e32 v10, 24, v10
	v_sub_u32_e32 v5, v5, v6
	v_or3_b32 v8, v8, v9, v10
	v_lshlrev_b32_e32 v9, 5, v3
	v_ashrrev_i16_sdwa v5, v222, sext(v5) dst_sel:DWORD dst_unused:UNUSED_PAD src0_sel:DWORD src1_sel:BYTE_0
	v_and_b32_e32 v9, 32, v9
	v_bfe_i32 v5, v5, 0, 16
	v_add_lshl_u32 v6, v9, v5, 1
	v_lshl_add_u32 v130, v8, 11, v6
	v_lshl_add_u32 v132, v7, 11, v6
	v_bfe_i32 v6, v2, 27, 1
	v_lshrrev_b32_e32 v6, 22, v6
	v_add_u32_e32 v6, v0, v6
	v_and_b32_e32 v6, 0xfffffc00, v6
	v_sub_u32_e32 v0, v0, v6
	v_lshrrev_b32_e32 v6, 4, v0
	v_ashrrev_i32_e32 v7, 31, v2
	v_bitop3_b32 v0, v6, v0, 32 bitop3:0x6c
	v_lshrrev_b32_e32 v7, 26, v7
	v_ashrrev_i32_e32 v6, 31, v0
	v_add_u32_e32 v7, v2, v7
	v_lshrrev_b32_e32 v6, 26, v6
	v_ashrrev_i32_e32 v7, 6, v7
	v_add_u32_e32 v8, v0, v6
	v_lshlrev_b32_e32 v9, 3, v7
	v_ashrrev_i32_e32 v6, 6, v8
	v_and_b32_e32 v9, -16, v9
	v_add_u32_e32 v9, v6, v9
	v_and_b32_e32 v10, 3, v6
	v_lshrrev_b32_e32 v11, 2, v9
	v_lshlrev_b32_e32 v12, 1, v9
	v_and_b32_e32 v8, 0xc0, v8
	s_ashr_i32 s8, s4, 6
	v_and_or_b32 v10, v9, s6, v10
	v_and_b32_e32 v11, 4, v11
	v_and_b32_e32 v12, 24, v12
	v_sub_u32_e32 v0, v0, v8
	s_ashr_i32 s5, s4, 8
	s_lshl_b32 s12, s8, 10
	v_or3_b32 v10, v10, v11, v12
	v_lshlrev_b32_e32 v11, 5, v7
	v_ashrrev_i16_sdwa v0, v222, sext(v0) dst_sel:DWORD dst_unused:UNUSED_PAD src0_sel:DWORD src1_sel:BYTE_0
	v_readlane_b32 s6, v254, 4
	v_readlane_b32 s9, v254, 51
	v_and_b32_e32 v11, 32, v11
	v_bfe_i32 v8, v0, 0, 16
	v_readlane_b32 s7, v254, 5
	s_add_u32 s20, s9, s6
	v_readlane_b32 s6, v254, 52
	v_add_lshl_u32 v11, v11, v8, 1
	s_addc_u32 s21, s6, s7
	s_add_i32 s26, s12, 0
	v_lshl_add_u32 v0, v10, 11, v11
	s_add_i32 m0, s26, 0x10000
	v_lshl_add_u32 v134, v9, 11, v11
	global_load_lds_dwordx4 v0, s[20:21]
	s_add_i32 m0, s26, 0x12000
	s_add_u32 s6, s20, 0x40000
	global_load_lds_dwordx4 v130, s[20:21]
	s_addc_u32 s7, s21, 0
	s_add_i32 m0, s26, 0x14000
	s_add_i32 s27, s26, 0x2000
	global_load_lds_dwordx4 v0, s[6:7]
	s_add_i32 m0, s26, 0x16000
	s_add_i32 s28, s26, 0x4000
	global_load_lds_dwordx4 v130, s[6:7]
	v_readlane_b32 s6, v254, 12
	s_mov_b32 m0, s26
	v_readlane_b32 s7, v254, 13
	s_add_i32 s29, s26, 0x6000
	s_cmp_eq_u32 s5, 1
	s_nop 2
	global_load_lds_dwordx4 v134, s[6:7]
	s_mov_b32 m0, s27
	s_nop 0
	global_load_lds_dwordx4 v132, s[6:7]
	v_readlane_b32 s6, v254, 14
	s_mov_b32 m0, s28
	v_readlane_b32 s7, v254, 15
	s_nop 4
	global_load_lds_dwordx4 v134, s[6:7]
	s_mov_b32 m0, s29
	s_nop 0
	global_load_lds_dwordx4 v132, s[6:7]
	s_cselect_b64 s[6:7], -1, 0
	s_cmp_lg_u32 s5, 1
	s_cbranch_scc1 .LBB0_199
	s_barrier

.LBB0_202:
	s_add_i32 s34, s34, 1
	v_readlane_b32 s4, v252, 15
	s_mul_i32 s4, s34, s4
	s_mul_hi_u32 s5, s34, s42
	s_add_i32 s5, s5, s4
	s_mul_i32 s4, s34, s42
	s_add_u32 s16, s4, s2
	s_addc_u32 s17, s5, s61
	v_mov_b64_e32 v[2:3], 0
	v_cmp_lt_i64_e64 s[4:5], s[16:17], v[2:3]
	v_mov_b64_e32 v[2:3], -1
	v_cmp_gt_i64_e32 vcc, s[16:17], v[2:3]
	s_cbranch_vccnz .LBB0_204
	s_ashr_i32 s10, s16, 31
	s_lshr_b32 s10, s10, 29
	s_add_i32 s10, s16, s10
	s_ashr_i32 s11, s10, 3
	s_and_b32 s10, s10, -8
	s_sub_i32 s10, s16, s10
	s_cmp_lt_i32 s10, 0
	s_cselect_b32 s14, 52, 51
	s_mul_i32 s10, s10, s14
	s_add_i32 s10, s10, s11
	s_mul_hi_i32 s11, s10, 0x2aaaaaab
	s_lshr_b32 s14, s11, 31
	s_ashr_i32 s11, s11, 3
	s_add_i32 s11, s11, s14
	s_lshl_b32 s14, s11, 3
	s_sub_i32 s15, 0x44, s14
	s_min_i32 s15, s15, 8
	s_abs_i32 s16, s15
	v_cvt_f32_u32_e32 v2, s16
	s_sub_i32 s18, 0, s16
	s_mul_i32 s11, s11, 48
	s_sub_i32 s11, s10, s11
	v_rcp_iflag_f32_e32 v2, v2
	s_abs_i32 s10, s11
	s_xor_b32 s17, s11, s15
	s_ashr_i32 s17, s17, 31
	v_mul_f32_e32 v2, 0x4f7ffffe, v2
	v_cvt_u32_f32_e32 v2, v2
	s_nop 0
	v_readfirstlane_b32 s19, v2
	s_mul_i32 s18, s18, s19
	s_mul_hi_u32 s18, s19, s18
	s_add_i32 s19, s19, s18
	s_mul_hi_u32 s18, s10, s19
	s_mul_i32 s19, s18, s16
	s_sub_i32 s10, s10, s19
	s_add_i32 s24, s18, 1
	s_sub_i32 s19, s10, s16
	s_cmp_ge_u32 s10, s16
	s_cselect_b32 s18, s24, s18
	s_cselect_b32 s10, s19, s10
	s_add_i32 s19, s18, 1
	s_cmp_ge_u32 s10, s16
	s_cselect_b32 s10, s19, s18
	s_xor_b32 s10, s10, s17
	s_sub_i32 s10, s10, s17
	s_mul_i32 s15, s10, s15
	s_sub_i32 s11, s11, s15
	s_add_i32 s14, s14, s11

.LBB0_211:
	s_waitcnt vmcnt(0)
	s_barrier
	v_readlane_b32 s6, v255, 10
	s_nop 0
	s_cmp_eq_u32 s6, 2
	s_cbranch_scc0 .LBB0_212
	s_mov_b32 s6, 0
	s_nop 0
	v_writelane_b32 v255, s6, 10
	s_branch .Lp1_to_p2

.LBB0_258:
	s_or_b64 exec, exec, s[40:41]
	s_xor_b64 s[4:5], s[38:39], -1
	v_writelane_b32 v254, s4, 53
	s_waitcnt lgkmcnt(0)
	s_barrier
	v_writelane_b32 v254, s5, 54
	s_nop 0
	v_readlane_b32 s4, v254, 47
	v_readlane_b32 s5, v254, 48
	s_xor_b64 s[4:5], s[4:5], -1
	v_writelane_b32 v254, s4, 55
	s_nop 1
	v_writelane_b32 v254, s5, 56
	v_readlane_b32 s6, v255, 10
	s_nop 0
	s_cmp_eq_u32 s6, 1
	s_cbranch_scc0 .Lp1_to_p2
	s_mov_b32 s6, 0
	s_nop 0
	v_writelane_b32 v255, s6, 10
	s_cmp_lt_u32 s2, 0x98
	s_cbranch_scc0 .Lp1_to_p2
	s_mov_b32 s6, 2
	s_nop 0
	v_writelane_b32 v255, s6, 10
	s_add_i32 s14, s2, 0x100
	s_branch .Lp1_pass
.Lp1_to_p2:
	v_readlane_b32 s4, v252, 38
	v_readlane_b32 s5, v252, 39
	s_andn2_b64 vcc, exec, s[4:5]
	s_cbranch_vccnz .LBB0_323
	s_lshl_b32 s4, s71, 11
	v_readlane_b32 s5, v252, 56
	s_or_b32 s12, s4, s5
	s_lshl_b32 s28, s71, 6
	s_lshl_b64 s[4:5], s[12:13], 4
	v_readlane_b32 s6, v252, 42
	s_add_u32 s14, s6, s4
	v_readlane_b32 s4, v252, 43
	s_addc_u32 s15, s4, s5
	s_lshl_b32 s6, s71, 1
	v_readlane_b32 s7, v252, 52
	s_add_i32 s8, s6, s7
	s_lshl_b32 s6, s8, 6
	v_readlane_b32 s7, v252, 48
	s_or_b32 s6, s6, s7
	s_mov_b32 s7, s13
	s_lshl_b32 s12, s71, 8
	s_lshl_b32 s4, s71, 10
	s_lshl_b64 s[6:7], s[6:7], 10
	v_readlane_b32 s9, v252, 46
	s_add_u32 s16, s9, s6
	v_readlane_b32 s6, v252, 47
	s_addc_u32 s17, s6, s7
	s_mul_i32 s6, s8, 0x300
	s_mov_b32 s7, s13
	s_lshl_b64 s[6:7], s[6:7], 2
	v_readlane_b32 s8, v252, 49
	s_mov_b32 s5, s13
	s_add_u32 s18, s8, s6
	v_readlane_b32 s6, v252, 50
	s_addc_u32 s19, s6, s7
	s_lshl_b64 s[20:21], s[4:5], 2
	v_readlane_b32 s29, v252, 6
	s_branch .LBB0_261
.LBB0_260:
	s_add_i32 s29, s29, s42
	s_cmpk_gt_i32 s29, 0x2ff
	s_cbranch_scc1 .LBB0_323
.LBB0_261:
	s_and_b32 s4, s29, 0xff
	s_lshr_b32 s5, s29, 8
	s_and_b32 s6, s4, 31
	s_lshr_b32 s4, s4, 5
	s_cmp_ge_u32 s6, 19
	s_cbranch_scc0 .Lmp3_busy
	s_mul_i32 s4, s4, 13
	s_add_i32 s4, s4, s6
	s_sub_i32 s4, s4, 19
	s_mov_b32 s8, s4
	s_mov_b32 s10, 7
	s_cmp_eq_u32 s5, 0
	s_cbranch_scc1 .LBB0_265
	s_add_i32 s8, s4, 0x68
	s_mov_b32 s10, 4
	s_cmp_eq_u32 s5, 1
	s_cbranch_scc1 .LBB0_265
	s_mov_b32 s10, 2
	s_branch .LBB0_265
.Lmp3_busy:
	s_mul_i32 s4, s4, 19
	s_add_i32 s4, s4, s6
	s_cmp_lt_u32 s4, 64
	s_cbranch_scc0 .Lmp3_b2
	s_cmp_eq_u32 s5, 0
	s_cbranch_scc0 .LBB0_260
	s_add_i32 s8, s4, 0xd0
	s_mov_b32 s10, 4
	s_branch .LBB0_265
.Lmp3_b2:
	s_cmp_lt_u32 s4, 0x80
	s_cbranch_scc0 .Lmp3_b3
	s_sub_i32 s4, s4, 64
	s_cmp_eq_u32 s5, 0
	s_cbranch_scc0 .Lmp3_b2r1
	s_add_i32 s8, s4, 0xd0
	s_mov_b32 s10, 3
	s_branch .LBB0_265
.Lmp3_b2r1:
	s_cmp_eq_u32 s5, 1
	s_cbranch_scc0 .LBB0_260
	s_cmp_lt_u32 s4, 32
	s_cbranch_scc0 .LBB0_260
	s_add_i32 s8, s4, 0xb0
	s_mov_b32 s10, 1
	s_branch .LBB0_265
.Lmp3_b3:
	s_sub_i32 s4, s4, 0x80
	s_mul_i32 s6, s5, 24
	s_add_i32 s8, s4, s6
	s_add_i32 s8, s8, 0x68
	s_mov_b32 s10, 1
